# two wait-state fixes (sweep-epilogue readlane, dot4 init) on top of cross-tile GEMM-1 streaming
# baseline (speedup 1.0000x reference)
.Lxp_syncda:
	s_and_b32 s84, s84, 0x3fff
	s_lshl_b32 s2, s84, 11
	s_add_u32 s2, s18, s2
	s_addc_u32 s3, s19, 0
	global_load_dwordx4 v[72:75], v252, s[2:3]
	global_load_dwordx4 v[64:67], v252, s[2:3] offset:1024
	s_lshl_b32 s2, s84, 2
	v_writelane_b32 v147, s2, 0
	v_writelane_b32 v2, s85, 0
	s_and_b32 s86, s86, 0x3fff
	s_lshl_b32 s2, s86, 11
	s_add_u32 s2, s18, s2
	s_addc_u32 s3, s19, 0
	global_load_dwordx4 v[76:79], v252, s[2:3]
	global_load_dwordx4 v[68:71], v252, s[2:3] offset:1024
	s_lshl_b32 s2, s86, 2
	v_writelane_b32 v147, s2, 1
	v_writelane_b32 v2, s87, 1
	s_and_b32 s88, s88, 0x3fff
	s_lshl_b32 s2, s88, 11
	s_add_u32 s2, s18, s2
	s_addc_u32 s3, s19, 0
	global_load_dwordx4 v[80:83], v252, s[2:3]
	global_load_dwordx4 v[4:7], v252, s[2:3] offset:1024
	s_lshl_b32 s2, s88, 2
	v_writelane_b32 v147, s2, 2
	v_writelane_b32 v2, s89, 2
	s_and_b32 s90, s90, 0x3fff
	s_lshl_b32 s2, s90, 11
	s_add_u32 s2, s18, s2
	s_addc_u32 s3, s19, 0
	global_load_dwordx4 v[84:87], v252, s[2:3]
	global_load_dwordx4 v[128:131], v252, s[2:3] offset:1024
	s_lshl_b32 s2, s90, 2
	v_writelane_b32 v147, s2, 3
	v_writelane_b32 v2, s91, 3
	global_load_dword v88, v147, s[44:45]
	global_load_dword v89, v147, s[46:47]
	v_dot4_i32_i8 v149, v8, v133, 0
	v_dot4_i32_i8 v150, v16, v133, 0
	v_dot4_i32_i8 v151, v32, v133, 0
	v_dot4_i32_i8 v148, v36, v133, 0
	s_nop 0
	v_dot4c_i32_i8_e32 v149, v9, v134
	v_dot4c_i32_i8_e32 v150, v17, v134
	v_dot4c_i32_i8_e32 v151, v33, v134
	v_dot4c_i32_i8_e32 v148, v37, v134
	v_dot4c_i32_i8_e32 v149, v10, v135
	v_dot4c_i32_i8_e32 v150, v18, v135
	v_dot4c_i32_i8_e32 v151, v34, v135
	v_dot4c_i32_i8_e32 v148, v38, v135
	v_dot4c_i32_i8_e32 v149, v11, v136
	v_dot4c_i32_i8_e32 v150, v19, v136
	v_dot4c_i32_i8_e32 v151, v35, v136
	v_dot4c_i32_i8_e32 v148, v39, v136
	s_add_i32 s3, s25, 3
	s_min_u32 s3, s3, 0x7f
	s_cmp_lt_u32 s3, 64
	s_cselect_b64 vcc, -1, 0
	s_nop 0
	v_cndmask_b32_e32 v249, v241, v240, vcc
	s_nop 1
	v_readlane_b32 s2, v249, s3
	s_and_b32 s3, s2, 31
	s_lshl_b32 s3, s3, 5
	s_bfe_u32 s94, s2, 0x20005
	s_lshl_b32 s2, s94, 11
	s_add_i32 s3, s3, s2
	s_load_dwordx8 s[84:91], s[36:37], s3
	v_cndmask_b32_e64 v143, v149, v150, s[0:1]
	v_cndmask_b32_e64 v144, v150, v149, s[0:1]
	v_cndmask_b32_e64 v145, v151, v148, s[0:1]
	v_cndmask_b32_e64 v146, v148, v151, s[0:1]
	s_nop 1
	v_add_u32_dpp v144, v143, v144 quad_perm:[1,0,3,2] row_mask:0xf bank_mask:0xf
	v_add_u32_dpp v146, v145, v146 quad_perm:[1,0,3,2] row_mask:0xf bank_mask:0xf
	s_nop 1
	v_cndmask_b32_e64 v143, v144, v146, s[6:7]
	v_cndmask_b32_e64 v145, v146, v144, s[6:7]
	s_nop 1
	v_add_u32_dpp v145, v143, v145 quad_perm:[2,3,0,1] row_mask:0xf bank_mask:0xf
	s_nop 1
	v_add_u32_dpp v145, v145, v145 row_ror:4 row_mask:0xf bank_mask:0xf
	s_nop 1
	v_add_u32_dpp v145, v145, v145 row_ror:8 row_mask:0xf bank_mask:0xf
	s_nop 1
	ds_bpermute_b32 v143, v126, v145
	s_waitcnt lgkmcnt(0)
	v_add_u32_e32 v145, v145, v143
	ds_bpermute_b32 v143, v127, v145
	s_waitcnt lgkmcnt(0)
	v_add_u32_e32 v145, v145, v143
	v_cvt_f32_i32_e32 v56, v145
	v_mul_f32_e32 v59, v138, v56
	v_mul_f32_e32 v59, v137, v59
	v_mul_f32_e32 v56, 0x3f3504f3, v59
	v_fma_f32 v143, |v56|, s66, v120
	v_fma_f32 v143, |v56|, v143, s67
	v_fma_f32 v143, |v56|, v143, s68
	v_fma_f32 v143, |v56|, v143, s69
	v_fma_f32 v143, |v56|, v143, s70
	v_fma_f32 v143, |v56|, v143, s71
	v_fma_f32 v143, |v56|, v143, |v56|
	v_mul_f32_e32 v144, 0xbfb8aa3b, v143
	v_fma_f32 v146, v143, s72, -v144
	v_rndne_f32_e32 v3, v144
	v_fmac_f32_e32 v146, 0xb2a5705f, v143
	v_sub_f32_e32 v144, v144, v3
	v_add_f32_e32 v144, v144, v146
	v_cvt_i32_f32_e32 v146, v3
	v_exp_f32_e32 v144, v144
	v_cmp_nlt_f32_e32 vcc, s73, v143
	v_ldexp_f32 v144, v144, v146
	s_nop 0
	v_cndmask_b32_e32 v144, 0, v144, vcc
	v_cmp_ngt_f32_e32 vcc, s74, v143
	s_nop 1
	v_cndmask_b32_e32 v143, v121, v144, vcc
	v_sub_f32_e32 v143, 1.0, v143
	v_mul_f32_e32 v168, v56, v56
	v_fmamk_f32 v169, v168, 0xba1345e1, v117
	v_fmaak_f32 v169, v168, v169, 0xbcdac9b8
	v_fmaak_f32 v169, v168, v169, 0x3de703be
	v_fmaak_f32 v169, v168, v169, 0xbec09330
	v_fmaak_f32 v168, v168, v169, 0x3e0375d0
	v_fma_f32 v168, |v56|, v168, |v56|
	v_cmp_nlt_f32_e64 vcc, |v56|, 1.0
	s_nop 1
	v_cndmask_b32_e32 v143, v168, v143, vcc
	v_bfi_b32 v146, s75, v143, v56
	v_mul_f32_e32 v145, 0.5, v59
	v_add_f32_e32 v146, 1.0, v146
	v_mul_f32_e32 v145, v145, v146
	v_mul_f32_e32 v144, v0, v145
	v_mul_f32_e32 v143, v139, v144
	s_nop 1
	v_readlane_b32 s40, v143, 0
	v_readlane_b32 s38, v143, 1
	v_readlane_b32 s42, v143, 2
	v_readlane_b32 s2, v143, 3
	s_nop 1
	v_add_f32_e32 v142, s40, v142
	v_add_f32_e32 v142, s38, v142
	v_add_f32_e32 v142, s42, v142
	v_add_f32_e32 v142, s2, v142
	v_cvt_f32_ubyte1_e32 v169, v40
	v_cvt_f32_ubyte0_e32 v168, v40
	v_pk_fma_f32 v[104:105], s[40:41], v[168:169], v[104:105] op_sel_hi:[0,1,1]
	v_cvt_f32_ubyte1_e32 v171, v44
	v_cvt_f32_ubyte0_e32 v170, v44
	v_pk_fma_f32 v[104:105], s[38:39], v[170:171], v[104:105] op_sel_hi:[0,1,1]
	v_cvt_f32_ubyte1_e32 v169, v48
	v_cvt_f32_ubyte0_e32 v168, v48
	v_pk_fma_f32 v[104:105], s[42:43], v[168:169], v[104:105] op_sel_hi:[0,1,1]
	v_cvt_f32_ubyte1_e32 v171, v52
	v_cvt_f32_ubyte0_e32 v170, v52
	v_pk_fma_f32 v[104:105], s[2:3], v[170:171], v[104:105] op_sel_hi:[0,1,1]
	v_cvt_f32_ubyte3_e32 v169, v40
	v_cvt_f32_ubyte2_e32 v168, v40
	v_pk_fma_f32 v[102:103], s[40:41], v[168:169], v[102:103] op_sel_hi:[0,1,1]
	v_cvt_f32_ubyte3_e32 v171, v44
	v_cvt_f32_ubyte2_e32 v170, v44
	v_pk_fma_f32 v[102:103], s[38:39], v[170:171], v[102:103] op_sel_hi:[0,1,1]
	v_cvt_f32_ubyte3_e32 v169, v48
	v_cvt_f32_ubyte2_e32 v168, v48
	v_pk_fma_f32 v[102:103], s[42:43], v[168:169], v[102:103] op_sel_hi:[0,1,1]
	v_cvt_f32_ubyte3_e32 v171, v52
	v_cvt_f32_ubyte2_e32 v170, v52
	v_pk_fma_f32 v[102:103], s[2:3], v[170:171], v[102:103] op_sel_hi:[0,1,1]
	v_cvt_f32_ubyte1_e32 v169, v41
	v_cvt_f32_ubyte0_e32 v168, v41
	v_pk_fma_f32 v[98:99], s[40:41], v[168:169], v[98:99] op_sel_hi:[0,1,1]
	v_cvt_f32_ubyte1_e32 v171, v45
	v_cvt_f32_ubyte0_e32 v170, v45
	v_pk_fma_f32 v[98:99], s[38:39], v[170:171], v[98:99] op_sel_hi:[0,1,1]
	v_cvt_f32_ubyte1_e32 v169, v49
	v_cvt_f32_ubyte0_e32 v168, v49
	v_pk_fma_f32 v[98:99], s[42:43], v[168:169], v[98:99] op_sel_hi:[0,1,1]
	v_cvt_f32_ubyte1_e32 v171, v53
	v_cvt_f32_ubyte0_e32 v170, v53
	v_pk_fma_f32 v[98:99], s[2:3], v[170:171], v[98:99] op_sel_hi:[0,1,1]
	v_cvt_f32_ubyte3_e32 v169, v41
	v_cvt_f32_ubyte2_e32 v168, v41
	v_pk_fma_f32 v[100:101], s[40:41], v[168:169], v[100:101] op_sel_hi:[0,1,1]
	v_cvt_f32_ubyte3_e32 v171, v45
	v_cvt_f32_ubyte2_e32 v170, v45
	v_pk_fma_f32 v[100:101], s[38:39], v[170:171], v[100:101] op_sel_hi:[0,1,1]
	v_cvt_f32_ubyte3_e32 v169, v49
	v_cvt_f32_ubyte2_e32 v168, v49
	v_pk_fma_f32 v[100:101], s[42:43], v[168:169], v[100:101] op_sel_hi:[0,1,1]
	v_cvt_f32_ubyte3_e32 v171, v53
	v_cvt_f32_ubyte2_e32 v170, v53
	v_pk_fma_f32 v[100:101], s[2:3], v[170:171], v[100:101] op_sel_hi:[0,1,1]
	v_cvt_f32_ubyte1_e32 v169, v42
	v_cvt_f32_ubyte0_e32 v168, v42
	v_pk_fma_f32 v[94:95], s[40:41], v[168:169], v[94:95] op_sel_hi:[0,1,1]
	v_cvt_f32_ubyte1_e32 v171, v46
	v_cvt_f32_ubyte0_e32 v170, v46
	v_pk_fma_f32 v[94:95], s[38:39], v[170:171], v[94:95] op_sel_hi:[0,1,1]
	v_cvt_f32_ubyte1_e32 v169, v50
	v_cvt_f32_ubyte0_e32 v168, v50
	v_pk_fma_f32 v[94:95], s[42:43], v[168:169], v[94:95] op_sel_hi:[0,1,1]
	v_cvt_f32_ubyte1_e32 v171, v54
	v_cvt_f32_ubyte0_e32 v170, v54
	v_pk_fma_f32 v[94:95], s[2:3], v[170:171], v[94:95] op_sel_hi:[0,1,1]
	v_cvt_f32_ubyte3_e32 v169, v42
	v_cvt_f32_ubyte2_e32 v168, v42
	v_pk_fma_f32 v[96:97], s[40:41], v[168:169], v[96:97] op_sel_hi:[0,1,1]
	v_cvt_f32_ubyte3_e32 v171, v46
	v_cvt_f32_ubyte2_e32 v170, v46
	v_pk_fma_f32 v[96:97], s[38:39], v[170:171], v[96:97] op_sel_hi:[0,1,1]
	v_cvt_f32_ubyte3_e32 v169, v50
	v_cvt_f32_ubyte2_e32 v168, v50
	v_pk_fma_f32 v[96:97], s[42:43], v[168:169], v[96:97] op_sel_hi:[0,1,1]
	v_cvt_f32_ubyte3_e32 v171, v54
	v_cvt_f32_ubyte2_e32 v170, v54
	v_pk_fma_f32 v[96:97], s[2:3], v[170:171], v[96:97] op_sel_hi:[0,1,1]
	v_cvt_f32_ubyte1_e32 v169, v43
	v_cvt_f32_ubyte0_e32 v168, v43
	v_pk_fma_f32 v[90:91], s[40:41], v[168:169], v[90:91] op_sel_hi:[0,1,1]
	v_cvt_f32_ubyte1_e32 v171, v47
	v_cvt_f32_ubyte0_e32 v170, v47
	v_pk_fma_f32 v[90:91], s[38:39], v[170:171], v[90:91] op_sel_hi:[0,1,1]
	v_cvt_f32_ubyte1_e32 v169, v51
	v_cvt_f32_ubyte0_e32 v168, v51
	v_pk_fma_f32 v[90:91], s[42:43], v[168:169], v[90:91] op_sel_hi:[0,1,1]
	v_cvt_f32_ubyte1_e32 v171, v55
	v_cvt_f32_ubyte0_e32 v170, v55
	v_pk_fma_f32 v[90:91], s[2:3], v[170:171], v[90:91] op_sel_hi:[0,1,1]
	v_cvt_f32_ubyte3_e32 v169, v43
	v_cvt_f32_ubyte2_e32 v168, v43
	v_pk_fma_f32 v[92:93], s[40:41], v[168:169], v[92:93] op_sel_hi:[0,1,1]
	v_cvt_f32_ubyte3_e32 v171, v47
	v_cvt_f32_ubyte2_e32 v170, v47
	v_pk_fma_f32 v[92:93], s[38:39], v[170:171], v[92:93] op_sel_hi:[0,1,1]
	v_cvt_f32_ubyte3_e32 v169, v51
	v_cvt_f32_ubyte2_e32 v168, v51
	v_pk_fma_f32 v[92:93], s[42:43], v[168:169], v[92:93] op_sel_hi:[0,1,1]
	v_cvt_f32_ubyte3_e32 v171, v55
	v_cvt_f32_ubyte2_e32 v170, v55
	v_pk_fma_f32 v[92:93], s[2:3], v[170:171], v[92:93] op_sel_hi:[0,1,1]
	s_waitcnt vmcnt(10) lgkmcnt(0)
	s_cmp_eq_u32 s80, s33
	s_cbranch_scc1 .Lxp_noswa
	s_lshl_b32 s2, s33, 12
	v_add_u32_e32 v249, s2, v248
	ds_write_b128 v249, v[90:93]
	ds_write_b128 v249, v[94:97] offset:1024
	ds_write_b128 v249, v[98:101] offset:2048
	ds_write_b128 v249, v[102:105] offset:3072
	v_cmp_eq_u32_e32 vcc, s33, v60
	s_nop 1
	v_cndmask_b32_e32 v243, v243, v142, vcc
	s_lshl_b32 s2, s80, 12
	v_add_u32_e32 v249, s2, v248
	ds_read_b128 v[90:93], v249
	ds_read_b128 v[94:97], v249 offset:1024
	ds_read_b128 v[98:101], v249 offset:2048
	ds_read_b128 v[102:105], v249 offset:3072
	s_nop 0
	v_readlane_b32 s2, v243, s80
	v_readlane_b32 s3, v244, s80
	s_nop 1
	v_mov_b32_e32 v142, s2
	v_mov_b32_e32 v137, s3
	s_cmp_eq_u32 s80, 0
	s_cbranch_scc1 .Lxp_lxqa0
	s_cmp_eq_u32 s80, 1
	s_cbranch_scc1 .Lxp_lxqa1
	s_cmp_eq_u32 s80, 2
	s_cbranch_scc1 .Lxp_lxqa2
	v_mov_b32_e32 v133, v236
	v_mov_b32_e32 v134, v237
	v_mov_b32_e32 v135, v238
	v_mov_b32_e32 v136, v239
	s_branch .Lxp_lxqad

.Lxp_syncdb:
	s_and_b32 s84, s84, 0x3fff
	s_lshl_b32 s2, s84, 11
	s_add_u32 s2, s18, s2
	s_addc_u32 s3, s19, 0
	global_load_dwordx4 v[8:11], v252, s[2:3]
	global_load_dwordx4 v[40:43], v252, s[2:3] offset:1024
	s_lshl_b32 s2, s84, 2
	v_writelane_b32 v147, s2, 0
	v_writelane_b32 v0, s85, 0
	s_and_b32 s86, s86, 0x3fff
	s_lshl_b32 s2, s86, 11
	s_add_u32 s2, s18, s2
	s_addc_u32 s3, s19, 0
	global_load_dwordx4 v[16:19], v252, s[2:3]
	global_load_dwordx4 v[44:47], v252, s[2:3] offset:1024
	s_lshl_b32 s2, s86, 2
	v_writelane_b32 v147, s2, 1
	v_writelane_b32 v0, s87, 1
	s_and_b32 s88, s88, 0x3fff
	s_lshl_b32 s2, s88, 11
	s_add_u32 s2, s18, s2
	s_addc_u32 s3, s19, 0
	global_load_dwordx4 v[32:35], v252, s[2:3]
	global_load_dwordx4 v[48:51], v252, s[2:3] offset:1024
	s_lshl_b32 s2, s88, 2
	v_writelane_b32 v147, s2, 2
	v_writelane_b32 v0, s89, 2
	s_and_b32 s90, s90, 0x3fff
	s_lshl_b32 s2, s90, 11
	s_add_u32 s2, s18, s2
	s_addc_u32 s3, s19, 0
	global_load_dwordx4 v[36:39], v252, s[2:3]
	global_load_dwordx4 v[52:55], v252, s[2:3] offset:1024
	s_lshl_b32 s2, s90, 2
	v_writelane_b32 v147, s2, 3
	v_writelane_b32 v0, s91, 3
	global_load_dword v138, v147, s[44:45]
	global_load_dword v139, v147, s[46:47]
	v_dot4_i32_i8 v149, v152, v133, 0
	v_dot4_i32_i8 v150, v156, v133, 0
	v_dot4_i32_i8 v151, v160, v133, 0
	v_dot4_i32_i8 v148, v164, v133, 0
	s_nop 0
	v_dot4c_i32_i8_e32 v149, v153, v134
	v_dot4c_i32_i8_e32 v150, v157, v134
	v_dot4c_i32_i8_e32 v151, v161, v134
	v_dot4c_i32_i8_e32 v148, v165, v134
	v_dot4c_i32_i8_e32 v149, v154, v135
	v_dot4c_i32_i8_e32 v150, v158, v135
	v_dot4c_i32_i8_e32 v151, v162, v135
	v_dot4c_i32_i8_e32 v148, v166, v135
	v_dot4c_i32_i8_e32 v149, v155, v136
	v_dot4c_i32_i8_e32 v150, v159, v136
	v_dot4c_i32_i8_e32 v151, v163, v136
	v_dot4c_i32_i8_e32 v148, v167, v136
	s_add_i32 s3, s25, 3
	s_min_u32 s3, s3, 0x7f
	s_cmp_lt_u32 s3, 64
	s_cselect_b64 vcc, -1, 0
	s_nop 0
	v_cndmask_b32_e32 v249, v241, v240, vcc
	s_nop 1
	v_readlane_b32 s2, v249, s3
	s_and_b32 s3, s2, 31
	s_lshl_b32 s3, s3, 5
	s_bfe_u32 s94, s2, 0x20005
	s_lshl_b32 s2, s94, 11
	s_add_i32 s3, s3, s2
	s_load_dwordx8 s[84:91], s[36:37], s3
	v_cndmask_b32_e64 v143, v149, v150, s[0:1]
	v_cndmask_b32_e64 v144, v150, v149, s[0:1]
	v_cndmask_b32_e64 v145, v151, v148, s[0:1]
	v_cndmask_b32_e64 v146, v148, v151, s[0:1]
	s_nop 1
	v_add_u32_dpp v144, v143, v144 quad_perm:[1,0,3,2] row_mask:0xf bank_mask:0xf
	v_add_u32_dpp v146, v145, v146 quad_perm:[1,0,3,2] row_mask:0xf bank_mask:0xf
	s_nop 1
	v_cndmask_b32_e64 v143, v144, v146, s[6:7]
	v_cndmask_b32_e64 v145, v146, v144, s[6:7]
	s_nop 1
	v_add_u32_dpp v145, v143, v145 quad_perm:[2,3,0,1] row_mask:0xf bank_mask:0xf
	s_nop 1
	v_add_u32_dpp v145, v145, v145 row_ror:4 row_mask:0xf bank_mask:0xf
	s_nop 1
	v_add_u32_dpp v145, v145, v145 row_ror:8 row_mask:0xf bank_mask:0xf
	s_nop 1
	ds_bpermute_b32 v143, v126, v145
	s_waitcnt lgkmcnt(0)
	v_add_u32_e32 v145, v145, v143
	ds_bpermute_b32 v143, v127, v145
	s_waitcnt lgkmcnt(0)
	v_add_u32_e32 v145, v145, v143
	v_cvt_f32_i32_e32 v56, v145
	v_mul_f32_e32 v59, v140, v56
	v_mul_f32_e32 v59, v137, v59
	v_mul_f32_e32 v56, 0x3f3504f3, v59
	v_fma_f32 v143, |v56|, s66, v120
	v_fma_f32 v143, |v56|, v143, s67
	v_fma_f32 v143, |v56|, v143, s68
	v_fma_f32 v143, |v56|, v143, s69
	v_fma_f32 v143, |v56|, v143, s70
	v_fma_f32 v143, |v56|, v143, s71
	v_fma_f32 v143, |v56|, v143, |v56|
	v_mul_f32_e32 v144, 0xbfb8aa3b, v143
	v_fma_f32 v146, v143, s72, -v144
	v_rndne_f32_e32 v3, v144
	v_fmac_f32_e32 v146, 0xb2a5705f, v143
	v_sub_f32_e32 v144, v144, v3
	v_add_f32_e32 v144, v144, v146
	v_cvt_i32_f32_e32 v146, v3
	v_exp_f32_e32 v144, v144
	v_cmp_nlt_f32_e32 vcc, s73, v143
	v_ldexp_f32 v144, v144, v146
	s_nop 0
	v_cndmask_b32_e32 v144, 0, v144, vcc
	v_cmp_ngt_f32_e32 vcc, s74, v143
	s_nop 1
	v_cndmask_b32_e32 v143, v121, v144, vcc
	v_sub_f32_e32 v143, 1.0, v143
	v_mul_f32_e32 v168, v56, v56
	v_fmamk_f32 v169, v168, 0xba1345e1, v117
	v_fmaak_f32 v169, v168, v169, 0xbcdac9b8
	v_fmaak_f32 v169, v168, v169, 0x3de703be
	v_fmaak_f32 v169, v168, v169, 0xbec09330
	v_fmaak_f32 v168, v168, v169, 0x3e0375d0
	v_fma_f32 v168, |v56|, v168, |v56|
	v_cmp_nlt_f32_e64 vcc, |v56|, 1.0
	s_nop 1
	v_cndmask_b32_e32 v143, v168, v143, vcc
	v_bfi_b32 v146, s75, v143, v56
	v_mul_f32_e32 v145, 0.5, v59
	v_add_f32_e32 v146, 1.0, v146
	v_mul_f32_e32 v145, v145, v146
	v_mul_f32_e32 v144, v1, v145
	v_mul_f32_e32 v143, v141, v144
	s_nop 1
	v_readlane_b32 s40, v143, 0
	v_readlane_b32 s38, v143, 1
	v_readlane_b32 s42, v143, 2
	v_readlane_b32 s2, v143, 3
	s_nop 1
	v_add_f32_e32 v142, s40, v142
	v_add_f32_e32 v142, s38, v142
	v_add_f32_e32 v142, s42, v142
	v_add_f32_e32 v142, s2, v142
	v_cvt_f32_ubyte1_e32 v169, v12
	v_cvt_f32_ubyte0_e32 v168, v12
	v_pk_fma_f32 v[104:105], s[40:41], v[168:169], v[104:105] op_sel_hi:[0,1,1]
	v_cvt_f32_ubyte1_e32 v171, v20
	v_cvt_f32_ubyte0_e32 v170, v20
	v_pk_fma_f32 v[104:105], s[38:39], v[170:171], v[104:105] op_sel_hi:[0,1,1]
	v_cvt_f32_ubyte1_e32 v169, v24
	v_cvt_f32_ubyte0_e32 v168, v24
	v_pk_fma_f32 v[104:105], s[42:43], v[168:169], v[104:105] op_sel_hi:[0,1,1]
	v_cvt_f32_ubyte1_e32 v171, v28
	v_cvt_f32_ubyte0_e32 v170, v28
	v_pk_fma_f32 v[104:105], s[2:3], v[170:171], v[104:105] op_sel_hi:[0,1,1]
	v_cvt_f32_ubyte3_e32 v169, v12
	v_cvt_f32_ubyte2_e32 v168, v12
	v_pk_fma_f32 v[102:103], s[40:41], v[168:169], v[102:103] op_sel_hi:[0,1,1]
	v_cvt_f32_ubyte3_e32 v171, v20
	v_cvt_f32_ubyte2_e32 v170, v20
	v_pk_fma_f32 v[102:103], s[38:39], v[170:171], v[102:103] op_sel_hi:[0,1,1]
	v_cvt_f32_ubyte3_e32 v169, v24
	v_cvt_f32_ubyte2_e32 v168, v24
	v_pk_fma_f32 v[102:103], s[42:43], v[168:169], v[102:103] op_sel_hi:[0,1,1]
	v_cvt_f32_ubyte3_e32 v171, v28
	v_cvt_f32_ubyte2_e32 v170, v28
	v_pk_fma_f32 v[102:103], s[2:3], v[170:171], v[102:103] op_sel_hi:[0,1,1]
	v_cvt_f32_ubyte1_e32 v169, v13
	v_cvt_f32_ubyte0_e32 v168, v13
	v_pk_fma_f32 v[98:99], s[40:41], v[168:169], v[98:99] op_sel_hi:[0,1,1]
	v_cvt_f32_ubyte1_e32 v171, v21
	v_cvt_f32_ubyte0_e32 v170, v21
	v_pk_fma_f32 v[98:99], s[38:39], v[170:171], v[98:99] op_sel_hi:[0,1,1]
	v_cvt_f32_ubyte1_e32 v169, v25
	v_cvt_f32_ubyte0_e32 v168, v25
	v_pk_fma_f32 v[98:99], s[42:43], v[168:169], v[98:99] op_sel_hi:[0,1,1]
	v_cvt_f32_ubyte1_e32 v171, v29
	v_cvt_f32_ubyte0_e32 v170, v29
	v_pk_fma_f32 v[98:99], s[2:3], v[170:171], v[98:99] op_sel_hi:[0,1,1]
	v_cvt_f32_ubyte3_e32 v169, v13
	v_cvt_f32_ubyte2_e32 v168, v13
	v_pk_fma_f32 v[100:101], s[40:41], v[168:169], v[100:101] op_sel_hi:[0,1,1]
	v_cvt_f32_ubyte3_e32 v171, v21
	v_cvt_f32_ubyte2_e32 v170, v21
	v_pk_fma_f32 v[100:101], s[38:39], v[170:171], v[100:101] op_sel_hi:[0,1,1]
	v_cvt_f32_ubyte3_e32 v169, v25
	v_cvt_f32_ubyte2_e32 v168, v25
	v_pk_fma_f32 v[100:101], s[42:43], v[168:169], v[100:101] op_sel_hi:[0,1,1]
	v_cvt_f32_ubyte3_e32 v171, v29
	v_cvt_f32_ubyte2_e32 v170, v29
	v_pk_fma_f32 v[100:101], s[2:3], v[170:171], v[100:101] op_sel_hi:[0,1,1]
	v_cvt_f32_ubyte1_e32 v169, v14
	v_cvt_f32_ubyte0_e32 v168, v14
	v_pk_fma_f32 v[94:95], s[40:41], v[168:169], v[94:95] op_sel_hi:[0,1,1]
	v_cvt_f32_ubyte1_e32 v171, v22
	v_cvt_f32_ubyte0_e32 v170, v22
	v_pk_fma_f32 v[94:95], s[38:39], v[170:171], v[94:95] op_sel_hi:[0,1,1]
	v_cvt_f32_ubyte1_e32 v169, v26
	v_cvt_f32_ubyte0_e32 v168, v26
	v_pk_fma_f32 v[94:95], s[42:43], v[168:169], v[94:95] op_sel_hi:[0,1,1]
	v_cvt_f32_ubyte1_e32 v171, v30
	v_cvt_f32_ubyte0_e32 v170, v30
	v_pk_fma_f32 v[94:95], s[2:3], v[170:171], v[94:95] op_sel_hi:[0,1,1]
	v_cvt_f32_ubyte3_e32 v169, v14
	v_cvt_f32_ubyte2_e32 v168, v14
	v_pk_fma_f32 v[96:97], s[40:41], v[168:169], v[96:97] op_sel_hi:[0,1,1]
	v_cvt_f32_ubyte3_e32 v171, v22
	v_cvt_f32_ubyte2_e32 v170, v22
	v_pk_fma_f32 v[96:97], s[38:39], v[170:171], v[96:97] op_sel_hi:[0,1,1]
	v_cvt_f32_ubyte3_e32 v169, v26
	v_cvt_f32_ubyte2_e32 v168, v26
	v_pk_fma_f32 v[96:97], s[42:43], v[168:169], v[96:97] op_sel_hi:[0,1,1]
	v_cvt_f32_ubyte3_e32 v171, v30
	v_cvt_f32_ubyte2_e32 v170, v30
	v_pk_fma_f32 v[96:97], s[2:3], v[170:171], v[96:97] op_sel_hi:[0,1,1]
	v_cvt_f32_ubyte1_e32 v169, v15
	v_cvt_f32_ubyte0_e32 v168, v15
	v_pk_fma_f32 v[90:91], s[40:41], v[168:169], v[90:91] op_sel_hi:[0,1,1]
	v_cvt_f32_ubyte1_e32 v171, v23
	v_cvt_f32_ubyte0_e32 v170, v23
	v_pk_fma_f32 v[90:91], s[38:39], v[170:171], v[90:91] op_sel_hi:[0,1,1]
	v_cvt_f32_ubyte1_e32 v169, v27
	v_cvt_f32_ubyte0_e32 v168, v27
	v_pk_fma_f32 v[90:91], s[42:43], v[168:169], v[90:91] op_sel_hi:[0,1,1]
	v_cvt_f32_ubyte1_e32 v171, v31
	v_cvt_f32_ubyte0_e32 v170, v31
	v_pk_fma_f32 v[90:91], s[2:3], v[170:171], v[90:91] op_sel_hi:[0,1,1]
	v_cvt_f32_ubyte3_e32 v169, v15
	v_cvt_f32_ubyte2_e32 v168, v15
	v_pk_fma_f32 v[92:93], s[40:41], v[168:169], v[92:93] op_sel_hi:[0,1,1]
	v_cvt_f32_ubyte3_e32 v171, v23
	v_cvt_f32_ubyte2_e32 v170, v23
	v_pk_fma_f32 v[92:93], s[38:39], v[170:171], v[92:93] op_sel_hi:[0,1,1]
	v_cvt_f32_ubyte3_e32 v169, v27
	v_cvt_f32_ubyte2_e32 v168, v27
	v_pk_fma_f32 v[92:93], s[42:43], v[168:169], v[92:93] op_sel_hi:[0,1,1]
	v_cvt_f32_ubyte3_e32 v171, v31
	v_cvt_f32_ubyte2_e32 v170, v31
	v_pk_fma_f32 v[92:93], s[2:3], v[170:171], v[92:93] op_sel_hi:[0,1,1]
	s_waitcnt vmcnt(10) lgkmcnt(0)
	s_cmp_eq_u32 s80, s33
	s_cbranch_scc1 .Lxp_noswb
	s_lshl_b32 s2, s33, 12
	v_add_u32_e32 v249, s2, v248
	ds_write_b128 v249, v[90:93]
	ds_write_b128 v249, v[94:97] offset:1024
	ds_write_b128 v249, v[98:101] offset:2048
	ds_write_b128 v249, v[102:105] offset:3072
	v_cmp_eq_u32_e32 vcc, s33, v60
	s_nop 1
	v_cndmask_b32_e32 v243, v243, v142, vcc
	s_lshl_b32 s2, s80, 12
	v_add_u32_e32 v249, s2, v248
	ds_read_b128 v[90:93], v249
	ds_read_b128 v[94:97], v249 offset:1024
	ds_read_b128 v[98:101], v249 offset:2048
	ds_read_b128 v[102:105], v249 offset:3072
	s_nop 0
	v_readlane_b32 s2, v243, s80
	v_readlane_b32 s3, v244, s80
	s_nop 1
	v_mov_b32_e32 v142, s2
	v_mov_b32_e32 v137, s3
	s_cmp_eq_u32 s80, 0
	s_cbranch_scc1 .Lxp_lxqb0
	s_cmp_eq_u32 s80, 1
	s_cbranch_scc1 .Lxp_lxqb1
	s_cmp_eq_u32 s80, 2
	s_cbranch_scc1 .Lxp_lxqb2
	v_mov_b32_e32 v133, v236
	v_mov_b32_e32 v134, v237
	v_mov_b32_e32 v135, v238
	v_mov_b32_e32 v136, v239
	s_branch .Lxp_lxqbd

.Lxp_syncdc:
	s_and_b32 s84, s84, 0x3fff
	s_lshl_b32 s2, s84, 11
	s_add_u32 s2, s18, s2
	s_addc_u32 s3, s19, 0
	global_load_dwordx4 v[152:155], v252, s[2:3]
	global_load_dwordx4 v[12:15], v252, s[2:3] offset:1024
	s_lshl_b32 s2, s84, 2
	v_writelane_b32 v147, s2, 0
	v_writelane_b32 v1, s85, 0
	s_and_b32 s86, s86, 0x3fff
	s_lshl_b32 s2, s86, 11
	s_add_u32 s2, s18, s2
	s_addc_u32 s3, s19, 0
	global_load_dwordx4 v[156:159], v252, s[2:3]
	global_load_dwordx4 v[20:23], v252, s[2:3] offset:1024
	s_lshl_b32 s2, s86, 2
	v_writelane_b32 v147, s2, 1
	v_writelane_b32 v1, s87, 1
	s_and_b32 s88, s88, 0x3fff
	s_lshl_b32 s2, s88, 11
	s_add_u32 s2, s18, s2
	s_addc_u32 s3, s19, 0
	global_load_dwordx4 v[160:163], v252, s[2:3]
	global_load_dwordx4 v[24:27], v252, s[2:3] offset:1024
	s_lshl_b32 s2, s88, 2
	v_writelane_b32 v147, s2, 2
	v_writelane_b32 v1, s89, 2
	s_and_b32 s90, s90, 0x3fff
	s_lshl_b32 s2, s90, 11
	s_add_u32 s2, s18, s2
	s_addc_u32 s3, s19, 0
	global_load_dwordx4 v[164:167], v252, s[2:3]
	global_load_dwordx4 v[28:31], v252, s[2:3] offset:1024
	s_lshl_b32 s2, s90, 2
	v_writelane_b32 v147, s2, 3
	v_writelane_b32 v1, s91, 3
	global_load_dword v140, v147, s[44:45]
	global_load_dword v141, v147, s[46:47]
	v_dot4_i32_i8 v149, v72, v133, 0
	v_dot4_i32_i8 v150, v76, v133, 0
	v_dot4_i32_i8 v151, v80, v133, 0
	v_dot4_i32_i8 v148, v84, v133, 0
	s_nop 0
	v_dot4c_i32_i8_e32 v149, v73, v134
	v_dot4c_i32_i8_e32 v150, v77, v134
	v_dot4c_i32_i8_e32 v151, v81, v134
	v_dot4c_i32_i8_e32 v148, v85, v134
	v_dot4c_i32_i8_e32 v149, v74, v135
	v_dot4c_i32_i8_e32 v150, v78, v135
	v_dot4c_i32_i8_e32 v151, v82, v135
	v_dot4c_i32_i8_e32 v148, v86, v135
	v_dot4c_i32_i8_e32 v149, v75, v136
	v_dot4c_i32_i8_e32 v150, v79, v136
	v_dot4c_i32_i8_e32 v151, v83, v136
	v_dot4c_i32_i8_e32 v148, v87, v136
	s_add_i32 s3, s25, 3
	s_min_u32 s3, s3, 0x7f
	s_cmp_lt_u32 s3, 64
	s_cselect_b64 vcc, -1, 0
	s_nop 0
	v_cndmask_b32_e32 v249, v241, v240, vcc
	s_nop 1
	v_readlane_b32 s2, v249, s3
	s_and_b32 s3, s2, 31
	s_lshl_b32 s3, s3, 5
	s_bfe_u32 s94, s2, 0x20005
	s_lshl_b32 s2, s94, 11
	s_add_i32 s3, s3, s2
	s_load_dwordx8 s[84:91], s[36:37], s3
	v_cndmask_b32_e64 v143, v149, v150, s[0:1]
	v_cndmask_b32_e64 v144, v150, v149, s[0:1]
	v_cndmask_b32_e64 v145, v151, v148, s[0:1]
	v_cndmask_b32_e64 v146, v148, v151, s[0:1]
	s_nop 1
	v_add_u32_dpp v144, v143, v144 quad_perm:[1,0,3,2] row_mask:0xf bank_mask:0xf
	v_add_u32_dpp v146, v145, v146 quad_perm:[1,0,3,2] row_mask:0xf bank_mask:0xf
	s_nop 1
	v_cndmask_b32_e64 v143, v144, v146, s[6:7]
	v_cndmask_b32_e64 v145, v146, v144, s[6:7]
	s_nop 1
	v_add_u32_dpp v145, v143, v145 quad_perm:[2,3,0,1] row_mask:0xf bank_mask:0xf
	s_nop 1
	v_add_u32_dpp v145, v145, v145 row_ror:4 row_mask:0xf bank_mask:0xf
	s_nop 1
	v_add_u32_dpp v145, v145, v145 row_ror:8 row_mask:0xf bank_mask:0xf
	s_nop 1
	ds_bpermute_b32 v143, v126, v145
	s_waitcnt lgkmcnt(0)
	v_add_u32_e32 v145, v145, v143
	ds_bpermute_b32 v143, v127, v145
	s_waitcnt lgkmcnt(0)
	v_add_u32_e32 v145, v145, v143
	v_cvt_f32_i32_e32 v56, v145
	v_mul_f32_e32 v59, v88, v56
	v_mul_f32_e32 v59, v137, v59
	v_mul_f32_e32 v56, 0x3f3504f3, v59
	v_fma_f32 v143, |v56|, s66, v120
	v_fma_f32 v143, |v56|, v143, s67
	v_fma_f32 v143, |v56|, v143, s68
	v_fma_f32 v143, |v56|, v143, s69
	v_fma_f32 v143, |v56|, v143, s70
	v_fma_f32 v143, |v56|, v143, s71
	v_fma_f32 v143, |v56|, v143, |v56|
	v_mul_f32_e32 v144, 0xbfb8aa3b, v143
	v_fma_f32 v146, v143, s72, -v144
	v_rndne_f32_e32 v3, v144
	v_fmac_f32_e32 v146, 0xb2a5705f, v143
	v_sub_f32_e32 v144, v144, v3
	v_add_f32_e32 v144, v144, v146
	v_cvt_i32_f32_e32 v146, v3
	v_exp_f32_e32 v144, v144
	v_cmp_nlt_f32_e32 vcc, s73, v143
	v_ldexp_f32 v144, v144, v146
	s_nop 0
	v_cndmask_b32_e32 v144, 0, v144, vcc
	v_cmp_ngt_f32_e32 vcc, s74, v143
	s_nop 1
	v_cndmask_b32_e32 v143, v121, v144, vcc
	v_sub_f32_e32 v143, 1.0, v143
	v_mul_f32_e32 v168, v56, v56
	v_fmamk_f32 v169, v168, 0xba1345e1, v117
	v_fmaak_f32 v169, v168, v169, 0xbcdac9b8
	v_fmaak_f32 v169, v168, v169, 0x3de703be
	v_fmaak_f32 v169, v168, v169, 0xbec09330
	v_fmaak_f32 v168, v168, v169, 0x3e0375d0
	v_fma_f32 v168, |v56|, v168, |v56|
	v_cmp_nlt_f32_e64 vcc, |v56|, 1.0
	s_nop 1
	v_cndmask_b32_e32 v143, v168, v143, vcc
	v_bfi_b32 v146, s75, v143, v56
	v_mul_f32_e32 v145, 0.5, v59
	v_add_f32_e32 v146, 1.0, v146
	v_mul_f32_e32 v145, v145, v146
	v_mul_f32_e32 v144, v2, v145
	v_mul_f32_e32 v143, v89, v144
	s_nop 1
	v_readlane_b32 s40, v143, 0
	v_readlane_b32 s38, v143, 1
	v_readlane_b32 s42, v143, 2
	v_readlane_b32 s2, v143, 3
	s_nop 1
	v_add_f32_e32 v142, s40, v142
	v_add_f32_e32 v142, s38, v142
	v_add_f32_e32 v142, s42, v142
	v_add_f32_e32 v142, s2, v142
	v_cvt_f32_ubyte1_e32 v169, v64
	v_cvt_f32_ubyte0_e32 v168, v64
	v_pk_fma_f32 v[104:105], s[40:41], v[168:169], v[104:105] op_sel_hi:[0,1,1]
	v_cvt_f32_ubyte1_e32 v171, v68
	v_cvt_f32_ubyte0_e32 v170, v68
	v_pk_fma_f32 v[104:105], s[38:39], v[170:171], v[104:105] op_sel_hi:[0,1,1]
	v_cvt_f32_ubyte1_e32 v169, v4
	v_cvt_f32_ubyte0_e32 v168, v4
	v_pk_fma_f32 v[104:105], s[42:43], v[168:169], v[104:105] op_sel_hi:[0,1,1]
	v_cvt_f32_ubyte1_e32 v171, v128
	v_cvt_f32_ubyte0_e32 v170, v128
	v_pk_fma_f32 v[104:105], s[2:3], v[170:171], v[104:105] op_sel_hi:[0,1,1]
	v_cvt_f32_ubyte3_e32 v169, v64
	v_cvt_f32_ubyte2_e32 v168, v64
	v_pk_fma_f32 v[102:103], s[40:41], v[168:169], v[102:103] op_sel_hi:[0,1,1]
	v_cvt_f32_ubyte3_e32 v171, v68
	v_cvt_f32_ubyte2_e32 v170, v68
	v_pk_fma_f32 v[102:103], s[38:39], v[170:171], v[102:103] op_sel_hi:[0,1,1]
	v_cvt_f32_ubyte3_e32 v169, v4
	v_cvt_f32_ubyte2_e32 v168, v4
	v_pk_fma_f32 v[102:103], s[42:43], v[168:169], v[102:103] op_sel_hi:[0,1,1]
	v_cvt_f32_ubyte3_e32 v171, v128
	v_cvt_f32_ubyte2_e32 v170, v128
	v_pk_fma_f32 v[102:103], s[2:3], v[170:171], v[102:103] op_sel_hi:[0,1,1]
	v_cvt_f32_ubyte1_e32 v169, v65
	v_cvt_f32_ubyte0_e32 v168, v65
	v_pk_fma_f32 v[98:99], s[40:41], v[168:169], v[98:99] op_sel_hi:[0,1,1]
	v_cvt_f32_ubyte1_e32 v171, v69
	v_cvt_f32_ubyte0_e32 v170, v69
	v_pk_fma_f32 v[98:99], s[38:39], v[170:171], v[98:99] op_sel_hi:[0,1,1]
	v_cvt_f32_ubyte1_e32 v169, v5
	v_cvt_f32_ubyte0_e32 v168, v5
	v_pk_fma_f32 v[98:99], s[42:43], v[168:169], v[98:99] op_sel_hi:[0,1,1]
	v_cvt_f32_ubyte1_e32 v171, v129
	v_cvt_f32_ubyte0_e32 v170, v129
	v_pk_fma_f32 v[98:99], s[2:3], v[170:171], v[98:99] op_sel_hi:[0,1,1]
	v_cvt_f32_ubyte3_e32 v169, v65
	v_cvt_f32_ubyte2_e32 v168, v65
	v_pk_fma_f32 v[100:101], s[40:41], v[168:169], v[100:101] op_sel_hi:[0,1,1]
	v_cvt_f32_ubyte3_e32 v171, v69
	v_cvt_f32_ubyte2_e32 v170, v69
	v_pk_fma_f32 v[100:101], s[38:39], v[170:171], v[100:101] op_sel_hi:[0,1,1]
	v_cvt_f32_ubyte3_e32 v169, v5
	v_cvt_f32_ubyte2_e32 v168, v5
	v_pk_fma_f32 v[100:101], s[42:43], v[168:169], v[100:101] op_sel_hi:[0,1,1]
	v_cvt_f32_ubyte3_e32 v171, v129
	v_cvt_f32_ubyte2_e32 v170, v129
	v_pk_fma_f32 v[100:101], s[2:3], v[170:171], v[100:101] op_sel_hi:[0,1,1]
	v_cvt_f32_ubyte1_e32 v169, v66
	v_cvt_f32_ubyte0_e32 v168, v66
	v_pk_fma_f32 v[94:95], s[40:41], v[168:169], v[94:95] op_sel_hi:[0,1,1]
	v_cvt_f32_ubyte1_e32 v171, v70
	v_cvt_f32_ubyte0_e32 v170, v70
	v_pk_fma_f32 v[94:95], s[38:39], v[170:171], v[94:95] op_sel_hi:[0,1,1]
	v_cvt_f32_ubyte1_e32 v169, v6
	v_cvt_f32_ubyte0_e32 v168, v6
	v_pk_fma_f32 v[94:95], s[42:43], v[168:169], v[94:95] op_sel_hi:[0,1,1]
	v_cvt_f32_ubyte1_e32 v171, v130
	v_cvt_f32_ubyte0_e32 v170, v130
	v_pk_fma_f32 v[94:95], s[2:3], v[170:171], v[94:95] op_sel_hi:[0,1,1]
	v_cvt_f32_ubyte3_e32 v169, v66
	v_cvt_f32_ubyte2_e32 v168, v66
	v_pk_fma_f32 v[96:97], s[40:41], v[168:169], v[96:97] op_sel_hi:[0,1,1]
	v_cvt_f32_ubyte3_e32 v171, v70
	v_cvt_f32_ubyte2_e32 v170, v70
	v_pk_fma_f32 v[96:97], s[38:39], v[170:171], v[96:97] op_sel_hi:[0,1,1]
	v_cvt_f32_ubyte3_e32 v169, v6
	v_cvt_f32_ubyte2_e32 v168, v6
	v_pk_fma_f32 v[96:97], s[42:43], v[168:169], v[96:97] op_sel_hi:[0,1,1]
	v_cvt_f32_ubyte3_e32 v171, v130
	v_cvt_f32_ubyte2_e32 v170, v130
	v_pk_fma_f32 v[96:97], s[2:3], v[170:171], v[96:97] op_sel_hi:[0,1,1]
	v_cvt_f32_ubyte1_e32 v169, v67
	v_cvt_f32_ubyte0_e32 v168, v67
	v_pk_fma_f32 v[90:91], s[40:41], v[168:169], v[90:91] op_sel_hi:[0,1,1]
	v_cvt_f32_ubyte1_e32 v171, v71
	v_cvt_f32_ubyte0_e32 v170, v71
	v_pk_fma_f32 v[90:91], s[38:39], v[170:171], v[90:91] op_sel_hi:[0,1,1]
	v_cvt_f32_ubyte1_e32 v169, v7
	v_cvt_f32_ubyte0_e32 v168, v7
	v_pk_fma_f32 v[90:91], s[42:43], v[168:169], v[90:91] op_sel_hi:[0,1,1]
	v_cvt_f32_ubyte1_e32 v171, v131
	v_cvt_f32_ubyte0_e32 v170, v131
	v_pk_fma_f32 v[90:91], s[2:3], v[170:171], v[90:91] op_sel_hi:[0,1,1]
	v_cvt_f32_ubyte3_e32 v169, v67
	v_cvt_f32_ubyte2_e32 v168, v67
	v_pk_fma_f32 v[92:93], s[40:41], v[168:169], v[92:93] op_sel_hi:[0,1,1]
	v_cvt_f32_ubyte3_e32 v171, v71
	v_cvt_f32_ubyte2_e32 v170, v71
	v_pk_fma_f32 v[92:93], s[38:39], v[170:171], v[92:93] op_sel_hi:[0,1,1]
	v_cvt_f32_ubyte3_e32 v169, v7
	v_cvt_f32_ubyte2_e32 v168, v7
	v_pk_fma_f32 v[92:93], s[42:43], v[168:169], v[92:93] op_sel_hi:[0,1,1]
	v_cvt_f32_ubyte3_e32 v171, v131
	v_cvt_f32_ubyte2_e32 v170, v131
	v_pk_fma_f32 v[92:93], s[2:3], v[170:171], v[92:93] op_sel_hi:[0,1,1]
	s_waitcnt vmcnt(10) lgkmcnt(0)
	s_cmp_eq_u32 s80, s33
	s_cbranch_scc1 .Lxp_noswc
	s_lshl_b32 s2, s33, 12
	v_add_u32_e32 v249, s2, v248
	ds_write_b128 v249, v[90:93]
	ds_write_b128 v249, v[94:97] offset:1024
	ds_write_b128 v249, v[98:101] offset:2048
	ds_write_b128 v249, v[102:105] offset:3072
	v_cmp_eq_u32_e32 vcc, s33, v60
	s_nop 1
	v_cndmask_b32_e32 v243, v243, v142, vcc
	s_lshl_b32 s2, s80, 12
	v_add_u32_e32 v249, s2, v248
	ds_read_b128 v[90:93], v249
	ds_read_b128 v[94:97], v249 offset:1024
	ds_read_b128 v[98:101], v249 offset:2048
	ds_read_b128 v[102:105], v249 offset:3072
	s_nop 0
	v_readlane_b32 s2, v243, s80
	v_readlane_b32 s3, v244, s80
	s_nop 1
	v_mov_b32_e32 v142, s2
	v_mov_b32_e32 v137, s3
	s_cmp_eq_u32 s80, 0
	s_cbranch_scc1 .Lxp_lxqc0
	s_cmp_eq_u32 s80, 1
	s_cbranch_scc1 .Lxp_lxqc1
	s_cmp_eq_u32 s80, 2
	s_cbranch_scc1 .Lxp_lxqc2
	v_mov_b32_e32 v133, v236
	v_mov_b32_e32 v134, v237
	v_mov_b32_e32 v135, v238
	v_mov_b32_e32 v136, v239
	s_branch .Lxp_lxqcd

.Lxp_out:
	s_lshl_b32 s2, s25, 12
	v_add_u32_e32 v249, s2, v248
	ds_read_b128 v[90:93], v249
	ds_read_b128 v[94:97], v249 offset:1024
	ds_read_b128 v[98:101], v249 offset:2048
	ds_read_b128 v[102:105], v249 offset:3072
	s_add_i32 s2, s32, s25
	s_lshl_b32 s3, s2, 11
	v_lshl_add_u32 v250, v60, 5, s3
	global_load_dwordx4 v[0:3], v250, s[16:17] offset:16
	global_load_dwordx4 v[4:7], v250, s[16:17]
	s_lshl_b32 s2, s2, 12
	v_lshl_add_u32 v251, v60, 6, s2
	v_readlane_b32 s3, v243, s25
	s_waitcnt vmcnt(0) lgkmcnt(0)
	s_nop 1
	v_mov_b32_e32 v142, s3
	v_lshlrev_b32_e32 v84, 16, v4
	v_and_b32_e32 v85, 0xffff0000, v4
	v_lshlrev_b32_e32 v86, 16, v5
	v_and_b32_e32 v87, 0xffff0000, v5
	v_lshlrev_b32_e32 v80, 16, v6
	v_and_b32_e32 v81, 0xffff0000, v6
	v_lshlrev_b32_e32 v82, 16, v7
	v_and_b32_e32 v83, 0xffff0000, v7
	v_lshlrev_b32_e32 v76, 16, v0
	v_and_b32_e32 v77, 0xffff0000, v0
	v_lshlrev_b32_e32 v78, 16, v1
	v_and_b32_e32 v79, 0xffff0000, v1
	v_lshlrev_b32_e32 v72, 16, v2
	v_and_b32_e32 v73, 0xffff0000, v2
	v_lshlrev_b32_e32 v74, 16, v3
	v_and_b32_e32 v75, 0xffff0000, v3
	v_pk_add_f32 v[8:9], v[104:105], v[84:85]
	v_pk_add_f32 v[10:11], v[102:103], v[86:87]
	v_fmac_f32_e32 v8, 0xc3000000, v142
	v_fmac_f32_e32 v9, 0xc3000000, v142
	v_fmac_f32_e32 v10, 0xc3000000, v142
	v_fmac_f32_e32 v11, 0xc3000000, v142
	global_store_dwordx4 v251, v[8:11], s[76:77]
	v_pk_add_f32 v[12:13], v[98:99], v[80:81]
	v_pk_add_f32 v[14:15], v[100:101], v[82:83]
	v_fmac_f32_e32 v12, 0xc3000000, v142
	v_fmac_f32_e32 v13, 0xc3000000, v142
	v_fmac_f32_e32 v14, 0xc3000000, v142
	v_fmac_f32_e32 v15, 0xc3000000, v142
	global_store_dwordx4 v251, v[12:15], s[76:77] offset:16
	v_pk_add_f32 v[16:17], v[94:95], v[76:77]
	v_pk_add_f32 v[18:19], v[96:97], v[78:79]
	v_fmac_f32_e32 v16, 0xc3000000, v142
	v_fmac_f32_e32 v17, 0xc3000000, v142
	v_fmac_f32_e32 v18, 0xc3000000, v142
	v_fmac_f32_e32 v19, 0xc3000000, v142
	global_store_dwordx4 v251, v[16:19], s[76:77] offset:32
	v_pk_add_f32 v[20:21], v[90:91], v[72:73]
	v_pk_add_f32 v[22:23], v[92:93], v[74:75]
	v_fmac_f32_e32 v20, 0xc3000000, v142
	v_fmac_f32_e32 v21, 0xc3000000, v142
	v_fmac_f32_e32 v22, 0xc3000000, v142
	v_fmac_f32_e32 v23, 0xc3000000, v142
	global_store_dwordx4 v251, v[20:23], s[76:77] offset:48
	s_add_i32 s25, s25, 1
	s_cmp_lt_u32 s25, 4
	s_cbranch_scc1 .Lxp_out
	s_waitcnt vmcnt(0)
	s_add_i32 s23, s23, 1
	s_cmp_lt_u32 s23, 8
	s_cbranch_scc1 .Lxp_sweep
	s_cmp_eq_u32 s82, 1
	s_cbranch_scc0 .Lxp_end
	v_bfrev_b32_e32 v245, 1
	s_mov_b64 exec, 1
	global_store_dword v[246:247], v245, off
	s_mov_b64 exec, -1
